# GEMM K-loop: LDS-DMA loads use SGPR base + 32-bit VGPR offset instead of a per-piece 64-bit VALU address add
# baseline (speedup 1.0000x reference)
; #define PG8_STAGE(bufoff, gbase, voff) do { _Pragma("unroll") for (int _i = 0; _i < 2; ++_i) \
;         __builtin_amdgcn_global_load_lds((const unsigned*)((const char*)(gbase) + (voff)[_i]), (PG8_LAS unsigned*)(lds + (bufoff) + ldsw + _i * 8192), 16, 0, 0); } while (0)
; #define PG8_LDA(dst, b, h) do { _Pragma("unroll") for (int m = 0; m < 4; ++m) _Pragma("unroll") for (int k = 0; k < 2; ++k) dst[m][k] = *(const PG8_LAS bf16x8*)(lds + PG8_SA(b, h) + aoff + m * 2048 + k * 1024); } while (0)
; #define PG8_LDB(dst, b, h) do { _Pragma("unroll") for (int n = 0; n < 2; ++n) _Pragma("unroll") for (int k = 0; k < 2; ++k) dst[n][k] = *(const PG8_LAS bf16x8*)(lds + PG8_SB(b, h) + boff + n * 2048 + k * 1024); } while (0)
; #define PG8_MMA(ai, bj, At, Bt) do { __builtin_amdgcn_s_setprio(1); _Pragma("unroll") for (int m = 0; m < 4; ++m) _Pragma("unroll") for (int n = 0; n < 2; ++n) _Pragma("unroll") for (int k = 0; k < 2; ++k) \
;         acc[ai][bj][m][n] = __builtin_amdgcn_mfma_f32_16x16x32_bf16(Bt[n][k], At[m][k], acc[ai][bj][m][n], 0, 0, 0); __builtin_amdgcn_s_setprio(0); } while (0)
; #define PG8_WAIT_V(n) asm volatile("s_waitcnt vmcnt(" #n ")" ::: "memory")
; #define PG8_WAIT_L(n) asm volatile("s_waitcnt lgkmcnt(" #n ")" ::: "memory")
; #define PG8_BAR __builtin_amdgcn_s_barrier()
; #define PG8_SCHED __builtin_amdgcn_sched_barrier(0)
; template <class Epi, class Sched, bool ALIGN_EPI = false, bool SP2 = false>
; __device__ __forceinline__ void gemm_phase(PG8_LAS unsigned char* lds, const Gemm g, const Sched& S, const Epi& E) {
;     ...
;             PG8_LDB(B0, 0, 0); PG8_LDB(B1, 0, 1); PG8_SCHED; PG8_LDA(At, 0, 0); PG8_STAGE(PG8_SA(1, 1), a1 + hstepB, voffA);
;             PG8_WAIT_V(8); PG8_WAIT_L(0); PG8_BAR; PG8_MMA(0, 0, At, B0); PG8_MMA(0, 1, At, B1); PG8_BAR; PG8_SCHED;
;             PG8_LDA(At, 0, 1); PG8_STAGE(PG8_SB(0, 0), b2, voffB); PG8_STAGE(PG8_SB(0, 1), b2 + hstepB, voffB); PG8_STAGE(PG8_SA(0, 0), a2, voffA);
;             PG8_WAIT_V(8); PG8_WAIT_L(0); PG8_BAR; PG8_MMA(1, 0, At, B0); PG8_MMA(1, 1, At, B1); PG8_BAR; PG8_SCHED;
.LBB0_372:
	s_add_i32 s71, s71, 2
	s_add_u32 s12, s6, 0x1fc000
	s_addc_u32 s13, s7, 0
	s_and_b64 s[26:27], exec, s[26:27]
	s_cselect_b32 s26, s69, s12
	s_cselect_b32 s27, s59, s13
	s_add_u32 vcc_lo, s26, 0x200000
	s_addc_u32 vcc_hi, s27, 0
	s_add_i32 s12, 0, 0x10000
	v_add_u32_e32 v142, s12, v144
	s_add_i32 s73, 0, 0x14000
	ds_read_b128 v[148:151], v142
	ds_read_b128 v[152:155], v142 offset:1024
	ds_read_b128 v[156:159], v142 offset:2048
	ds_read_b128 v[160:163], v142 offset:3072
	v_add_u32_e32 v142, s73, v144
	ds_read_b128 v[164:167], v142
	ds_read_b128 v[168:171], v142 offset:1024
	ds_read_b128 v[172:175], v142 offset:2048
	ds_read_b128 v[176:179], v142 offset:3072
	s_add_i32 m0, s45, 0xc000
	ds_read_b128 v[180:183], v146
	ds_read_b128 v[184:187], v146 offset:1024
	ds_read_b128 v[188:191], v146 offset:2048
	ds_read_b128 v[192:195], v146 offset:3072
	ds_read_b128 v[196:199], v146 offset:4096
	ds_read_b128 v[200:203], v146 offset:5120
	ds_read_b128 v[204:207], v146 offset:6144
	ds_read_b128 v[222:225], v146 offset:7168
	global_load_lds_dwordx4 v138, s[6:7]
	s_add_i32 m0, s45, 0xe000
	s_nop 0
	global_load_lds_dwordx4 v140, s[6:7]
	s_waitcnt vmcnt(8)
	s_waitcnt lgkmcnt(0)
	s_barrier
	s_setprio 1
	s_waitcnt lgkmcnt(0)
	v_mfma_f32_16x16x32_bf16 v[126:129], v[148:151], v[180:183], v[126:129]
	v_mfma_f32_16x16x32_bf16 v[122:125], v[156:159], v[180:183], v[122:125]
	v_mfma_f32_16x16x32_bf16 v[114:117], v[148:151], v[188:191], v[114:117]
	v_mfma_f32_16x16x32_bf16 v[106:109], v[156:159], v[188:191], v[106:109]
	v_mfma_f32_16x16x32_bf16 v[98:101], v[148:151], v[196:199], v[98:101]
	v_mfma_f32_16x16x32_bf16 v[90:93], v[156:159], v[196:199], v[90:93]
	v_mfma_f32_16x16x32_bf16 v[82:85], v[148:151], v[204:207], v[82:85]
	v_mfma_f32_16x16x32_bf16 v[74:77], v[156:159], v[204:207], v[74:77]
	v_mfma_f32_16x16x32_bf16 v[126:129], v[152:155], v[184:187], v[126:129]
	v_mfma_f32_16x16x32_bf16 v[122:125], v[160:163], v[184:187], v[122:125]
	v_mfma_f32_16x16x32_bf16 v[114:117], v[152:155], v[192:195], v[114:117]
	v_mfma_f32_16x16x32_bf16 v[106:109], v[160:163], v[192:195], v[106:109]
	v_mfma_f32_16x16x32_bf16 v[98:101], v[152:155], v[200:203], v[98:101]
	v_mfma_f32_16x16x32_bf16 v[90:93], v[160:163], v[200:203], v[90:93]
	v_mfma_f32_16x16x32_bf16 v[82:85], v[152:155], v[222:225], v[82:85]
	v_mfma_f32_16x16x32_bf16 v[74:77], v[160:163], v[222:225], v[74:77]
	s_setprio 0
	s_setprio 1
	v_mfma_f32_16x16x32_bf16 v[118:121], v[164:167], v[180:183], v[118:121]
	v_mfma_f32_16x16x32_bf16 v[110:113], v[172:175], v[180:183], v[110:113]
	v_mfma_f32_16x16x32_bf16 v[102:105], v[164:167], v[188:191], v[102:105]
	v_mfma_f32_16x16x32_bf16 v[94:97], v[172:175], v[188:191], v[94:97]
	v_mfma_f32_16x16x32_bf16 v[86:89], v[164:167], v[196:199], v[86:89]
	v_mfma_f32_16x16x32_bf16 v[78:81], v[172:175], v[196:199], v[78:81]
	v_mfma_f32_16x16x32_bf16 v[70:73], v[164:167], v[204:207], v[70:73]
	v_mfma_f32_16x16x32_bf16 v[66:69], v[172:175], v[204:207], v[66:69]
	v_mfma_f32_16x16x32_bf16 v[118:121], v[168:171], v[184:187], v[118:121]
	v_mfma_f32_16x16x32_bf16 v[110:113], v[176:179], v[184:187], v[110:113]
	v_mfma_f32_16x16x32_bf16 v[102:105], v[168:171], v[192:195], v[102:105]
	v_mfma_f32_16x16x32_bf16 v[94:97], v[176:179], v[192:195], v[94:97]
	v_mfma_f32_16x16x32_bf16 v[86:89], v[168:171], v[200:203], v[86:89]
	v_mfma_f32_16x16x32_bf16 v[78:81], v[176:179], v[200:203], v[78:81]
	v_mfma_f32_16x16x32_bf16 v[70:73], v[168:171], v[222:225], v[70:73]
	v_mfma_f32_16x16x32_bf16 v[66:69], v[176:179], v[222:225], v[66:69]
	s_setprio 0
	s_barrier
	s_add_i32 s12, s12, s23
	s_mov_b32 m0, s12
	ds_read_b128 v[180:183], v146 offset:16384
	ds_read_b128 v[184:187], v146 offset:17408
	ds_read_b128 v[188:191], v146 offset:18432
	ds_read_b128 v[192:195], v146 offset:19456
	ds_read_b128 v[196:199], v146 offset:20480
	ds_read_b128 v[200:203], v146 offset:21504
	ds_read_b128 v[204:207], v146 offset:22528
	ds_read_b128 v[222:225], v146 offset:23552
	global_load_lds_dwordx4 v134, s[74:75]
	s_add_i32 m0, s12, 0x2000
	s_add_u32 s12, s74, 0x4000
	s_addc_u32 s13, s75, 0
	s_add_i32 s73, s73, s23
	global_load_lds_dwordx4 v130, s[74:75]
	s_mov_b32 m0, s73
	s_nop 0
	global_load_lds_dwordx4 v134, s[12:13]
	s_add_i32 m0, s73, 0x2000
	s_nop 0
	global_load_lds_dwordx4 v130, s[12:13]
	s_mov_b32 m0, s45
	s_nop 0
	global_load_lds_dwordx4 v136, s[26:27]
	s_mov_b32 m0, s49
	s_nop 0
	global_load_lds_dwordx4 v132, s[26:27]
	s_waitcnt vmcnt(8)
	s_waitcnt lgkmcnt(0)
	s_barrier
	s_setprio 1
	s_waitcnt lgkmcnt(0)
	v_mfma_f32_16x16x32_bf16 v[62:65], v[148:151], v[180:183], v[62:65]
	v_mfma_f32_16x16x32_bf16 v[58:61], v[156:159], v[180:183], v[58:61]
	v_mfma_f32_16x16x32_bf16 v[46:49], v[148:151], v[188:191], v[46:49]
	v_mfma_f32_16x16x32_bf16 v[42:45], v[156:159], v[188:191], v[42:45]
	v_mfma_f32_16x16x32_bf16 v[30:33], v[148:151], v[196:199], v[30:33]
	v_mfma_f32_16x16x32_bf16 v[26:29], v[156:159], v[196:199], v[26:29]
	v_mfma_f32_16x16x32_bf16 v[14:17], v[148:151], v[204:207], v[14:17]
	v_mfma_f32_16x16x32_bf16 v[10:13], v[156:159], v[204:207], v[10:13]
	v_mfma_f32_16x16x32_bf16 v[62:65], v[152:155], v[184:187], v[62:65]
	v_mfma_f32_16x16x32_bf16 v[58:61], v[160:163], v[184:187], v[58:61]
	v_mfma_f32_16x16x32_bf16 v[46:49], v[152:155], v[192:195], v[46:49]
	v_mfma_f32_16x16x32_bf16 v[42:45], v[160:163], v[192:195], v[42:45]
	v_mfma_f32_16x16x32_bf16 v[30:33], v[152:155], v[200:203], v[30:33]
	v_mfma_f32_16x16x32_bf16 v[26:29], v[160:163], v[200:203], v[26:29]
	v_mfma_f32_16x16x32_bf16 v[14:17], v[152:155], v[222:225], v[14:17]
	v_mfma_f32_16x16x32_bf16 v[10:13], v[160:163], v[222:225], v[10:13]
	s_setprio 0
	s_setprio 1
	v_mfma_f32_16x16x32_bf16 v[54:57], v[164:167], v[180:183], v[54:57]
	v_mfma_f32_16x16x32_bf16 v[50:53], v[172:175], v[180:183], v[50:53]
	v_mfma_f32_16x16x32_bf16 v[38:41], v[164:167], v[188:191], v[38:41]
	v_mfma_f32_16x16x32_bf16 v[34:37], v[172:175], v[188:191], v[34:37]
	v_mfma_f32_16x16x32_bf16 v[22:25], v[164:167], v[196:199], v[22:25]
	v_mfma_f32_16x16x32_bf16 v[18:21], v[172:175], v[196:199], v[18:21]
	v_mfma_f32_16x16x32_bf16 v[6:9], v[164:167], v[204:207], v[6:9]
	v_mfma_f32_16x16x32_bf16 v[2:5], v[172:175], v[204:207], v[2:5]
	v_mfma_f32_16x16x32_bf16 v[54:57], v[168:171], v[184:187], v[54:57]
	v_mfma_f32_16x16x32_bf16 v[50:53], v[176:179], v[184:187], v[50:53]
	v_mfma_f32_16x16x32_bf16 v[38:41], v[168:171], v[192:195], v[38:41]
	v_mfma_f32_16x16x32_bf16 v[34:37], v[176:179], v[192:195], v[34:37]
	v_mfma_f32_16x16x32_bf16 v[22:25], v[168:171], v[200:203], v[22:25]
	v_mfma_f32_16x16x32_bf16 v[18:21], v[176:179], v[200:203], v[18:21]
	v_mfma_f32_16x16x32_bf16 v[6:9], v[168:171], v[222:225], v[6:9]
	v_mfma_f32_16x16x32_bf16 v[2:5], v[176:179], v[222:225], v[2:5]
	s_setprio 0
	s_barrier
; #define PG8_STAGE(bufoff, gbase, voff) do { _Pragma("unroll") for (int _i = 0; _i < 2; ++_i) \
;         __builtin_amdgcn_global_load_lds((const unsigned*)((const char*)(gbase) + (voff)[_i]), (PG8_LAS unsigned*)(lds + (bufoff) + ldsw + _i * 8192), 16, 0, 0); } while (0)
; #define PG8_LDA(dst, b, h) do { _Pragma("unroll") for (int m = 0; m < 4; ++m) _Pragma("unroll") for (int k = 0; k < 2; ++k) dst[m][k] = *(const PG8_LAS bf16x8*)(lds + PG8_SA(b, h) + aoff + m * 2048 + k * 1024); } while (0)
; #define PG8_LDB(dst, b, h) do { _Pragma("unroll") for (int n = 0; n < 2; ++n) _Pragma("unroll") for (int k = 0; k < 2; ++k) dst[n][k] = *(const PG8_LAS bf16x8*)(lds + PG8_SB(b, h) + boff + n * 2048 + k * 1024); } while (0)
; #define PG8_MMA(ai, bj, At, Bt) do { __builtin_amdgcn_s_setprio(1); _Pragma("unroll") for (int m = 0; m < 4; ++m) _Pragma("unroll") for (int n = 0; n < 2; ++n) _Pragma("unroll") for (int k = 0; k < 2; ++k) \
;         acc[ai][bj][m][n] = __builtin_amdgcn_mfma_f32_16x16x32_bf16(Bt[n][k], At[m][k], acc[ai][bj][m][n], 0, 0, 0); __builtin_amdgcn_s_setprio(0); } while (0)
; #define PG8_WAIT_V(n) asm volatile("s_waitcnt vmcnt(" #n ")" ::: "memory")
; #define PG8_WAIT_L(n) asm volatile("s_waitcnt lgkmcnt(" #n ")" ::: "memory")
; #define PG8_BAR __builtin_amdgcn_s_barrier()
; template <class Epi, class Sched, bool ALIGN_EPI = false, bool SP2 = false>
; __device__ __forceinline__ void gemm_phase(PG8_LAS unsigned char* lds, const Gemm g, const Sched& S, const Epi& E) {
;     ...
;         for (int t = 0; t < nt; t += 2) {
;             const bool last = (t == nt - 2);
;             const char* a1 = cA + (size_t)(t + 1) * kstepA;
;             const char* a2 = last ? nA : cA + (size_t)(t + 2) * kstepA; const char* b2 = last ? nB : cB + (size_t)(t + 2) * kstepB;
;             const char* a3 = a2 + kstepA; const char* b3 = b2 + kstepB;
;     ...
;             PG8_LDB(B0, 1, 0); PG8_LDB(B1, 1, 1); PG8_SCHED; PG8_LDA(At, 1, 0); PG8_STAGE(PG8_SA(0, 1), a2 + hstepB, voffA);
;             PG8_WAIT_V(8); PG8_WAIT_L(0); PG8_BAR; PG8_MMA(0, 0, At, B0); PG8_MMA(0, 1, At, B1); PG8_BAR; PG8_SCHED;
;             PG8_LDA(At, 1, 1); PG8_STAGE(PG8_SB(1, 0), b3, voffB); PG8_STAGE(PG8_SB(1, 1), b3 + hstepB, voffB); PG8_STAGE(PG8_SA(1, 0), a3, voffA);
;             PG8_WAIT_V(8); PG8_WAIT_L(0); PG8_BAR; PG8_MMA(1, 0, At, B0); PG8_MMA(1, 1, At, B1); PG8_BAR; PG8_SCHED;
	s_add_i32 s73, 0, 0x18000
	v_add_u32_e32 v142, s73, v144
	s_add_i32 s61, 0, 0x1c000
	ds_read_b128 v[148:151], v142
	ds_read_b128 v[152:155], v142 offset:1024
	ds_read_b128 v[156:159], v142 offset:2048
	ds_read_b128 v[160:163], v142 offset:3072
	v_add_u32_e32 v142, s61, v144
	ds_read_b128 v[164:167], v142
	ds_read_b128 v[168:171], v142 offset:1024
	ds_read_b128 v[172:175], v142 offset:2048
	ds_read_b128 v[176:179], v142 offset:3072
	s_add_u32 s12, s26, 0x4000
	s_addc_u32 s13, s27, 0
	s_mov_b32 m0, s52
	ds_read_b128 v[180:183], v146 offset:32768
	ds_read_b128 v[184:187], v146 offset:33792
	ds_read_b128 v[188:191], v146 offset:34816
	ds_read_b128 v[192:195], v146 offset:35840
	ds_read_b128 v[196:199], v146 offset:36864
	ds_read_b128 v[200:203], v146 offset:37888
	ds_read_b128 v[204:207], v146 offset:38912
	ds_read_b128 v[222:225], v146 offset:39936
	global_load_lds_dwordx4 v136, s[12:13]
	s_mov_b32 m0, s53
	s_nop 0
	global_load_lds_dwordx4 v132, s[12:13]
	s_waitcnt vmcnt(8)
	s_waitcnt lgkmcnt(0)
	s_barrier
	s_setprio 1
	s_waitcnt lgkmcnt(0)
	v_mfma_f32_16x16x32_bf16 v[126:129], v[148:151], v[180:183], v[126:129]
	v_mfma_f32_16x16x32_bf16 v[122:125], v[156:159], v[180:183], v[122:125]
	v_mfma_f32_16x16x32_bf16 v[114:117], v[148:151], v[188:191], v[114:117]
	v_mfma_f32_16x16x32_bf16 v[106:109], v[156:159], v[188:191], v[106:109]
	v_mfma_f32_16x16x32_bf16 v[98:101], v[148:151], v[196:199], v[98:101]
	v_mfma_f32_16x16x32_bf16 v[90:93], v[156:159], v[196:199], v[90:93]
	v_mfma_f32_16x16x32_bf16 v[82:85], v[148:151], v[204:207], v[82:85]
	v_mfma_f32_16x16x32_bf16 v[74:77], v[156:159], v[204:207], v[74:77]
	v_mfma_f32_16x16x32_bf16 v[126:129], v[152:155], v[184:187], v[126:129]
	v_mfma_f32_16x16x32_bf16 v[122:125], v[160:163], v[184:187], v[122:125]
	v_mfma_f32_16x16x32_bf16 v[114:117], v[152:155], v[192:195], v[114:117]
	v_mfma_f32_16x16x32_bf16 v[106:109], v[160:163], v[192:195], v[106:109]
	v_mfma_f32_16x16x32_bf16 v[98:101], v[152:155], v[200:203], v[98:101]
	v_mfma_f32_16x16x32_bf16 v[90:93], v[160:163], v[200:203], v[90:93]
	v_mfma_f32_16x16x32_bf16 v[82:85], v[152:155], v[222:225], v[82:85]
	v_mfma_f32_16x16x32_bf16 v[74:77], v[160:163], v[222:225], v[74:77]
	s_setprio 0
	s_setprio 1
	v_mfma_f32_16x16x32_bf16 v[118:121], v[164:167], v[180:183], v[118:121]
	v_mfma_f32_16x16x32_bf16 v[110:113], v[172:175], v[180:183], v[110:113]
	v_mfma_f32_16x16x32_bf16 v[102:105], v[164:167], v[188:191], v[102:105]
	v_mfma_f32_16x16x32_bf16 v[94:97], v[172:175], v[188:191], v[94:97]
	v_mfma_f32_16x16x32_bf16 v[86:89], v[164:167], v[196:199], v[86:89]
	v_mfma_f32_16x16x32_bf16 v[78:81], v[172:175], v[196:199], v[78:81]
	v_mfma_f32_16x16x32_bf16 v[70:73], v[164:167], v[204:207], v[70:73]
	v_mfma_f32_16x16x32_bf16 v[66:69], v[172:175], v[204:207], v[66:69]
	v_mfma_f32_16x16x32_bf16 v[118:121], v[168:171], v[184:187], v[118:121]
	v_mfma_f32_16x16x32_bf16 v[110:113], v[176:179], v[184:187], v[110:113]
	v_mfma_f32_16x16x32_bf16 v[102:105], v[168:171], v[192:195], v[102:105]
	v_mfma_f32_16x16x32_bf16 v[94:97], v[176:179], v[192:195], v[94:97]
	v_mfma_f32_16x16x32_bf16 v[86:89], v[168:171], v[200:203], v[86:89]
	v_mfma_f32_16x16x32_bf16 v[78:81], v[176:179], v[200:203], v[78:81]
	v_mfma_f32_16x16x32_bf16 v[70:73], v[168:171], v[222:225], v[70:73]
	v_mfma_f32_16x16x32_bf16 v[66:69], v[176:179], v[222:225], v[66:69]
	s_setprio 0
	s_barrier
	s_add_u32 s12, s74, s54
	s_addc_u32 s13, s75, 0
	s_add_i32 s26, s73, s23
	s_mov_b32 m0, s26
	ds_read_b128 v[180:183], v146 offset:49152
	ds_read_b128 v[184:187], v146 offset:50176
	ds_read_b128 v[188:191], v146 offset:51200
	ds_read_b128 v[192:195], v146 offset:52224
	ds_read_b128 v[196:199], v146 offset:53248
	ds_read_b128 v[200:203], v146 offset:54272
	ds_read_b128 v[204:207], v146 offset:55296
	ds_read_b128 v[222:225], v146 offset:56320
	global_load_lds_dwordx4 v134, s[12:13]
	s_add_i32 m0, s26, 0x2000
	s_nop 0
	global_load_lds_dwordx4 v130, s[12:13]
	s_add_u32 s12, s12, 0x4000
	s_addc_u32 s13, s13, 0
	s_add_i32 s26, s61, s23
	s_mov_b32 m0, s26
	s_nop 0
	global_load_lds_dwordx4 v134, s[12:13]
	s_add_i32 m0, s26, 0x2000
	s_nop 0
	global_load_lds_dwordx4 v130, s[12:13]
	s_mov_b32 m0, s55
	s_nop 0
	global_load_lds_dwordx4 v136, vcc
	s_mov_b32 m0, s20
	s_nop 0
	global_load_lds_dwordx4 v132, vcc
	s_waitcnt vmcnt(8)
	s_waitcnt lgkmcnt(0)
	s_barrier
	s_setprio 1
	s_waitcnt lgkmcnt(0)
	v_mfma_f32_16x16x32_bf16 v[62:65], v[148:151], v[180:183], v[62:65]
	v_mfma_f32_16x16x32_bf16 v[58:61], v[156:159], v[180:183], v[58:61]
	v_mfma_f32_16x16x32_bf16 v[46:49], v[148:151], v[188:191], v[46:49]
	v_mfma_f32_16x16x32_bf16 v[42:45], v[156:159], v[188:191], v[42:45]
	v_mfma_f32_16x16x32_bf16 v[30:33], v[148:151], v[196:199], v[30:33]
	v_mfma_f32_16x16x32_bf16 v[26:29], v[156:159], v[196:199], v[26:29]
	v_mfma_f32_16x16x32_bf16 v[14:17], v[148:151], v[204:207], v[14:17]
	v_mfma_f32_16x16x32_bf16 v[10:13], v[156:159], v[204:207], v[10:13]
	v_mfma_f32_16x16x32_bf16 v[62:65], v[152:155], v[184:187], v[62:65]
	v_mfma_f32_16x16x32_bf16 v[58:61], v[160:163], v[184:187], v[58:61]
	v_mfma_f32_16x16x32_bf16 v[46:49], v[152:155], v[192:195], v[46:49]
	v_mfma_f32_16x16x32_bf16 v[42:45], v[160:163], v[192:195], v[42:45]
	v_mfma_f32_16x16x32_bf16 v[30:33], v[152:155], v[200:203], v[30:33]
	v_mfma_f32_16x16x32_bf16 v[26:29], v[160:163], v[200:203], v[26:29]
	v_mfma_f32_16x16x32_bf16 v[14:17], v[152:155], v[222:225], v[14:17]
	v_mfma_f32_16x16x32_bf16 v[10:13], v[160:163], v[222:225], v[10:13]
	s_setprio 0
	s_setprio 1
	v_mfma_f32_16x16x32_bf16 v[54:57], v[164:167], v[180:183], v[54:57]
	v_mfma_f32_16x16x32_bf16 v[50:53], v[172:175], v[180:183], v[50:53]
	v_mfma_f32_16x16x32_bf16 v[38:41], v[164:167], v[188:191], v[38:41]
	v_mfma_f32_16x16x32_bf16 v[34:37], v[172:175], v[188:191], v[34:37]
	v_mfma_f32_16x16x32_bf16 v[22:25], v[164:167], v[196:199], v[22:25]
	v_mfma_f32_16x16x32_bf16 v[18:21], v[172:175], v[196:199], v[18:21]
	v_mfma_f32_16x16x32_bf16 v[6:9], v[164:167], v[204:207], v[6:9]
	v_mfma_f32_16x16x32_bf16 v[2:5], v[172:175], v[204:207], v[2:5]
	v_mfma_f32_16x16x32_bf16 v[54:57], v[168:171], v[184:187], v[54:57]
	v_mfma_f32_16x16x32_bf16 v[50:53], v[176:179], v[184:187], v[50:53]
	v_mfma_f32_16x16x32_bf16 v[38:41], v[168:171], v[192:195], v[38:41]
	v_mfma_f32_16x16x32_bf16 v[34:37], v[176:179], v[192:195], v[34:37]
	v_mfma_f32_16x16x32_bf16 v[22:25], v[168:171], v[200:203], v[22:25]
	v_mfma_f32_16x16x32_bf16 v[18:21], v[176:179], v[200:203], v[18:21]
	v_mfma_f32_16x16x32_bf16 v[6:9], v[168:171], v[222:225], v[6:9]
	v_mfma_f32_16x16x32_bf16 v[2:5], v[176:179], v[222:225], v[2:5]
	s_setprio 0
	s_barrier
	s_add_u32 s76, s76, s58
	s_addc_u32 s77, s77, 0
	s_add_u32 s6, s6, 0x400000
	s_addc_u32 s7, s7, 0
	s_cmp_ge_u32 s71, s25
	s_cbranch_scc1 .LBB0_375
